# P8 ticket hand-off waits only for the prefetched atomic (vmcnt(4)), not for the wave's previous tile stores
# speedup vs baseline: 1.0024x; 1.0024x over previous
; DEVINL void phase8(const Params& p) {
;     ...
;   {
;     unsigned* ticket = (unsigned*)(ws + O_BAR);
;     volatile int* slot = (volatile int*)(dynsmem + 120000);
;     for (;;) {
;       if (tid == 0) *slot = (int)atomicAdd(ticket, 1u);
;       __syncthreads();
;       const int t = *slot;
;       if (t >= 16 * 128 * 3) break;
.LBB0_903:
	s_add_u32 s10, s92, 0x10c00000
	s_addc_u32 s11, s93, 0
	s_mov_b64 s[4:5], src_shared_base
	s_add_u32 s8, s92, 0x8c00000
	v_cmp_eq_u32_e32 vcc, 0, v0
	s_addc_u32 s9, s93, 0
	s_mov_b64 s[6:7], 0
	v_mov_b32_e32 v1, 0
	s_add_i32 s3, 16, 0x1d4c0
	s_movk_i32 s4, 0x1800
	s_movk_i32 s18, 0xfff
	s_movk_i32 s19, 0x404
	s_and_saveexec_b64 s[12:13], vcc
	s_cbranch_execz .Lp8_pf
	v_mov_b32_e32 v2, 1
	global_atomic_add v60, v1, v2, s[96:97] sc0
	s_waitcnt vmcnt(0)

; DEVINL void phase8(const Params& p) {
;     ...
;       if (tid == 0) *slot = (int)atomicAdd(ticket, 1u);
;       __syncthreads();
;       const int t = *slot;
.LBB0_906:
	s_and_saveexec_b64 s[12:13], vcc
	s_cbranch_execz .LBB0_910
	s_waitcnt vmcnt(4)
	v_mov_b32_e32 v0, v60
	v_mov_b32_e32 v2, s3
	ds_write_b32 v2, v0
	s_waitcnt lgkmcnt(0)
